# k20 + uhy_t: in-projection channel-major bf16 scatter transposed in registers (v_permlane32_swap + v_permlane16_swap) so each 2-byte store writes one contiguous 128-B line
# baseline (speedup 1.0000x reference)
; __device__ __forceinline__ bf16_t f2bf(float f) { return (bf16_t)cvtpk(f, 0.f); }
;     __device__ __forceinline__ void operator()(const f32x4 (&acc)[2][2][4][2], const pg8::Unit& u, int wr, int wc, int, int) const {
;     ...
;         if (u.pn < 6) {
;             bf16_t* cp = uhy + (size_t)(u.pn * 256 + wc * 32 + 8 * fq) * NTOK + row0;
; #pragma unroll
;             for (int bj = 0; bj < 2; ++bj)
; #pragma unroll
;                 for (int n = 0; n < 2; ++n)
; #pragma unroll
;                     for (int j = 0; j < 4; ++j) { bf16_t* q = cp + (size_t)(bj * HALF + 4 * n + j) * NTOK;
; #pragma unroll
;                         for (int ai = 0; ai < 2; ++ai)
; #pragma unroll
;                             for (int m = 0; m < 4; ++m) q[ai * HALF + m * 16] = f2bf(acc[ai][bj][m][n][j]);
;                         asm volatile("" ::: "memory"); }
.LBB0_179:
	s_andn2_b64 vcc, exec, s[20:21]
	s_cbranch_vccnz .LBB0_172
	s_or_b32 s13, s13, s41
	v_add_u32_e32 v152, s13, v150
	v_mov_b64_e32 v[150:151], s[6:7]
	v_mad_i64_i32 v[150:151], s[20:21], v152, s48, v[150:151]
	v_lshl_add_u64 v[144:145], v[144:145], 1, v[150:151]
	v_mbcnt_lo_u32_b32 v150, -1, 0
	v_mbcnt_hi_u32_b32 v150, -1, v150
	v_lshrrev_b32_e32 v150, 4, v150
	s_mov_b32 s98, 0xffec0020
	s_mov_b32 s99, 0
	v_mad_i64_i32 v[144:145], s[20:21], v150, s98, v[144:145]
	v_permlane32_swap_b32_e32 v124, v116
	v_permlane32_swap_b32_e32 v120, v112
	v_permlane32_swap_b32_e32 v108, v96
	v_permlane32_swap_b32_e32 v104, v88
	v_permlane16_swap_b32_e32 v124, v120
	v_permlane16_swap_b32_e32 v116, v112
	v_permlane16_swap_b32_e32 v108, v104
	v_permlane16_swap_b32_e32 v96, v88
	s_mov_b32 s98, 0x0
	v_cvt_pk_bf16_f32 v124, v124, s0
	v_cvt_pk_bf16_f32 v108, v108, s0
	v_lshl_add_u64 v[150:151], v[144:145], 0, s[98:99]
	global_store_short v[150:151], v124, off
	global_store_short v[150:151], v108, off offset:256
	s_mov_b32 s98, 0x140000
	v_cvt_pk_bf16_f32 v120, v120, s0
	v_cvt_pk_bf16_f32 v104, v104, s0
	v_lshl_add_u64 v[150:151], v[144:145], 0, s[98:99]
	global_store_short v[150:151], v120, off
	global_store_short v[150:151], v104, off offset:256
	s_mov_b32 s98, 0x280000
	v_cvt_pk_bf16_f32 v116, v116, s0
	v_cvt_pk_bf16_f32 v96, v96, s0
	v_lshl_add_u64 v[150:151], v[144:145], 0, s[98:99]
	global_store_short v[150:151], v116, off
	global_store_short v[150:151], v96, off offset:256
	s_mov_b32 s98, 0x3c0000
	v_cvt_pk_bf16_f32 v112, v112, s0
	v_cvt_pk_bf16_f32 v88, v88, s0
	v_lshl_add_u64 v[150:151], v[144:145], 0, s[98:99]
	global_store_short v[150:151], v112, off
	global_store_short v[150:151], v88, off offset:256
	v_permlane32_swap_b32_e32 v125, v117
	v_permlane32_swap_b32_e32 v121, v113
	v_permlane32_swap_b32_e32 v109, v97
	v_permlane32_swap_b32_e32 v105, v89
	v_permlane16_swap_b32_e32 v125, v121
	v_permlane16_swap_b32_e32 v117, v113
	v_permlane16_swap_b32_e32 v109, v105
	v_permlane16_swap_b32_e32 v97, v89
	s_mov_b32 s98, 0x28000
	v_cvt_pk_bf16_f32 v125, v125, s0
	v_cvt_pk_bf16_f32 v109, v109, s0
	v_lshl_add_u64 v[150:151], v[144:145], 0, s[98:99]
	global_store_short v[150:151], v125, off
	global_store_short v[150:151], v109, off offset:256
	s_mov_b32 s98, 0x168000
	v_cvt_pk_bf16_f32 v121, v121, s0
	v_cvt_pk_bf16_f32 v105, v105, s0
	v_lshl_add_u64 v[150:151], v[144:145], 0, s[98:99]
	global_store_short v[150:151], v121, off
	global_store_short v[150:151], v105, off offset:256
	s_mov_b32 s98, 0x2a8000
	v_cvt_pk_bf16_f32 v117, v117, s0
	v_cvt_pk_bf16_f32 v97, v97, s0
	v_lshl_add_u64 v[150:151], v[144:145], 0, s[98:99]
	global_store_short v[150:151], v117, off
	global_store_short v[150:151], v97, off offset:256
	s_mov_b32 s98, 0x3e8000
	v_cvt_pk_bf16_f32 v113, v113, s0
	v_cvt_pk_bf16_f32 v89, v89, s0
	v_lshl_add_u64 v[150:151], v[144:145], 0, s[98:99]
	global_store_short v[150:151], v113, off
	global_store_short v[150:151], v89, off offset:256
	v_permlane32_swap_b32_e32 v126, v118
	v_permlane32_swap_b32_e32 v122, v114
	v_permlane32_swap_b32_e32 v110, v98
	v_permlane32_swap_b32_e32 v106, v90
	v_permlane16_swap_b32_e32 v126, v122
	v_permlane16_swap_b32_e32 v118, v114
	v_permlane16_swap_b32_e32 v110, v106
	v_permlane16_swap_b32_e32 v98, v90
	s_mov_b32 s98, 0x50000
	v_cvt_pk_bf16_f32 v126, v126, s0
	v_cvt_pk_bf16_f32 v110, v110, s0
	v_lshl_add_u64 v[150:151], v[144:145], 0, s[98:99]
	global_store_short v[150:151], v126, off
	global_store_short v[150:151], v110, off offset:256
	s_mov_b32 s98, 0x190000
	v_cvt_pk_bf16_f32 v122, v122, s0
	v_cvt_pk_bf16_f32 v106, v106, s0
	v_lshl_add_u64 v[150:151], v[144:145], 0, s[98:99]
	global_store_short v[150:151], v122, off
	global_store_short v[150:151], v106, off offset:256
	s_mov_b32 s98, 0x2d0000
	v_cvt_pk_bf16_f32 v118, v118, s0
	v_cvt_pk_bf16_f32 v98, v98, s0
	v_lshl_add_u64 v[150:151], v[144:145], 0, s[98:99]
	global_store_short v[150:151], v118, off
	global_store_short v[150:151], v98, off offset:256
	s_mov_b32 s98, 0x410000
	v_cvt_pk_bf16_f32 v114, v114, s0
	v_cvt_pk_bf16_f32 v90, v90, s0
	v_lshl_add_u64 v[150:151], v[144:145], 0, s[98:99]
	global_store_short v[150:151], v114, off
	global_store_short v[150:151], v90, off offset:256
	v_permlane32_swap_b32_e32 v127, v119
	v_permlane32_swap_b32_e32 v123, v115
	v_permlane32_swap_b32_e32 v111, v99
	v_permlane32_swap_b32_e32 v107, v91
	v_permlane16_swap_b32_e32 v127, v123
	v_permlane16_swap_b32_e32 v119, v115
	v_permlane16_swap_b32_e32 v111, v107
	v_permlane16_swap_b32_e32 v99, v91
	s_mov_b32 s98, 0x78000
	v_cvt_pk_bf16_f32 v127, v127, s0
	v_cvt_pk_bf16_f32 v111, v111, s0
	v_lshl_add_u64 v[150:151], v[144:145], 0, s[98:99]
	global_store_short v[150:151], v127, off
	global_store_short v[150:151], v111, off offset:256
	s_mov_b32 s98, 0x1b8000
	v_cvt_pk_bf16_f32 v123, v123, s0
	v_cvt_pk_bf16_f32 v107, v107, s0
	v_lshl_add_u64 v[150:151], v[144:145], 0, s[98:99]
	global_store_short v[150:151], v123, off
	global_store_short v[150:151], v107, off offset:256
	s_mov_b32 s98, 0x2f8000
	v_cvt_pk_bf16_f32 v119, v119, s0
	v_cvt_pk_bf16_f32 v99, v99, s0
	v_lshl_add_u64 v[150:151], v[144:145], 0, s[98:99]
	global_store_short v[150:151], v119, off
	global_store_short v[150:151], v99, off offset:256
	s_mov_b32 s98, 0x438000
	v_cvt_pk_bf16_f32 v115, v115, s0
	v_cvt_pk_bf16_f32 v91, v91, s0
	v_lshl_add_u64 v[150:151], v[144:145], 0, s[98:99]
	global_store_short v[150:151], v115, off
	global_store_short v[150:151], v91, off offset:256
	v_permlane32_swap_b32_e32 v100, v84
	v_permlane32_swap_b32_e32 v92, v80
	v_permlane32_swap_b32_e32 v76, v68
	v_permlane32_swap_b32_e32 v72, v64
; __device__ __forceinline__ bf16_t f2bf(float f) { return (bf16_t)cvtpk(f, 0.f); }
;     __device__ __forceinline__ void operator()(const f32x4 (&acc)[2][2][4][2], const pg8::Unit& u, int wr, int wc, int, int) const {
;     ...
;         if (u.pn < 6) {
;             bf16_t* cp = uhy + (size_t)(u.pn * 256 + wc * 32 + 8 * fq) * NTOK + row0;
; #pragma unroll
;             for (int bj = 0; bj < 2; ++bj)
; #pragma unroll
;                 for (int n = 0; n < 2; ++n)
; #pragma unroll
;                     for (int j = 0; j < 4; ++j) { bf16_t* q = cp + (size_t)(bj * HALF + 4 * n + j) * NTOK;
; #pragma unroll
;                         for (int ai = 0; ai < 2; ++ai)
; #pragma unroll
;                             for (int m = 0; m < 4; ++m) q[ai * HALF + m * 16] = f2bf(acc[ai][bj][m][n][j]);
;                         asm volatile("" ::: "memory"); }
	v_permlane16_swap_b32_e32 v100, v92
	v_permlane16_swap_b32_e32 v84, v80
	v_permlane16_swap_b32_e32 v76, v72
	v_permlane16_swap_b32_e32 v68, v64
	s_mov_b32 s98, 0xa0000
	v_cvt_pk_bf16_f32 v100, v100, s0
	v_cvt_pk_bf16_f32 v76, v76, s0
	v_lshl_add_u64 v[150:151], v[144:145], 0, s[98:99]
	global_store_short v[150:151], v100, off
	global_store_short v[150:151], v76, off offset:256
	s_mov_b32 s98, 0x1e0000
	v_cvt_pk_bf16_f32 v92, v92, s0
	v_cvt_pk_bf16_f32 v72, v72, s0
	v_lshl_add_u64 v[150:151], v[144:145], 0, s[98:99]
	global_store_short v[150:151], v92, off
	global_store_short v[150:151], v72, off offset:256
	s_mov_b32 s98, 0x320000
	v_cvt_pk_bf16_f32 v84, v84, s0
	v_cvt_pk_bf16_f32 v68, v68, s0
	v_lshl_add_u64 v[150:151], v[144:145], 0, s[98:99]
	global_store_short v[150:151], v84, off
	global_store_short v[150:151], v68, off offset:256
	s_mov_b32 s98, 0x460000
	v_cvt_pk_bf16_f32 v80, v80, s0
	v_cvt_pk_bf16_f32 v64, v64, s0
	v_lshl_add_u64 v[150:151], v[144:145], 0, s[98:99]
	global_store_short v[150:151], v80, off
	global_store_short v[150:151], v64, off offset:256
	v_permlane32_swap_b32_e32 v101, v85
	v_permlane32_swap_b32_e32 v93, v81
	v_permlane32_swap_b32_e32 v77, v69
	v_permlane32_swap_b32_e32 v73, v65
	v_permlane16_swap_b32_e32 v101, v93
	v_permlane16_swap_b32_e32 v85, v81
	v_permlane16_swap_b32_e32 v77, v73
	v_permlane16_swap_b32_e32 v69, v65
	s_mov_b32 s98, 0xc8000
	v_cvt_pk_bf16_f32 v101, v101, s0
	v_cvt_pk_bf16_f32 v77, v77, s0
	v_lshl_add_u64 v[150:151], v[144:145], 0, s[98:99]
	global_store_short v[150:151], v101, off
	global_store_short v[150:151], v77, off offset:256
	s_mov_b32 s98, 0x208000
	v_cvt_pk_bf16_f32 v93, v93, s0
	v_cvt_pk_bf16_f32 v73, v73, s0
	v_lshl_add_u64 v[150:151], v[144:145], 0, s[98:99]
	global_store_short v[150:151], v93, off
	global_store_short v[150:151], v73, off offset:256
	s_mov_b32 s98, 0x348000
	v_cvt_pk_bf16_f32 v85, v85, s0
	v_cvt_pk_bf16_f32 v69, v69, s0
	v_lshl_add_u64 v[150:151], v[144:145], 0, s[98:99]
	global_store_short v[150:151], v85, off
	global_store_short v[150:151], v69, off offset:256
	s_mov_b32 s98, 0x488000
	v_cvt_pk_bf16_f32 v81, v81, s0
	v_cvt_pk_bf16_f32 v65, v65, s0
	v_lshl_add_u64 v[150:151], v[144:145], 0, s[98:99]
	global_store_short v[150:151], v81, off
	global_store_short v[150:151], v65, off offset:256
	v_permlane32_swap_b32_e32 v102, v86
	v_permlane32_swap_b32_e32 v94, v82
	v_permlane32_swap_b32_e32 v78, v70
	v_permlane32_swap_b32_e32 v74, v66
	v_permlane16_swap_b32_e32 v102, v94
	v_permlane16_swap_b32_e32 v86, v82
	v_permlane16_swap_b32_e32 v78, v74
	v_permlane16_swap_b32_e32 v70, v66
	s_mov_b32 s98, 0xf0000
	v_cvt_pk_bf16_f32 v102, v102, s0
	v_cvt_pk_bf16_f32 v78, v78, s0
	v_lshl_add_u64 v[150:151], v[144:145], 0, s[98:99]
	global_store_short v[150:151], v102, off
	global_store_short v[150:151], v78, off offset:256
	s_mov_b32 s98, 0x230000
	v_cvt_pk_bf16_f32 v94, v94, s0
	v_cvt_pk_bf16_f32 v74, v74, s0
	v_lshl_add_u64 v[150:151], v[144:145], 0, s[98:99]
	global_store_short v[150:151], v94, off
	global_store_short v[150:151], v74, off offset:256
	s_mov_b32 s98, 0x370000
	v_cvt_pk_bf16_f32 v86, v86, s0
	v_cvt_pk_bf16_f32 v70, v70, s0
	v_lshl_add_u64 v[150:151], v[144:145], 0, s[98:99]
	global_store_short v[150:151], v86, off
	global_store_short v[150:151], v70, off offset:256
	s_mov_b32 s98, 0x4b0000
	v_cvt_pk_bf16_f32 v82, v82, s0
	v_cvt_pk_bf16_f32 v66, v66, s0
	v_lshl_add_u64 v[150:151], v[144:145], 0, s[98:99]
	global_store_short v[150:151], v82, off
	global_store_short v[150:151], v66, off offset:256
	v_permlane32_swap_b32_e32 v103, v87
	v_permlane32_swap_b32_e32 v95, v83
	v_permlane32_swap_b32_e32 v79, v71
	v_permlane32_swap_b32_e32 v75, v67
	v_permlane16_swap_b32_e32 v103, v95
	v_permlane16_swap_b32_e32 v87, v83
	v_permlane16_swap_b32_e32 v79, v75
	v_permlane16_swap_b32_e32 v71, v67
	s_mov_b32 s98, 0x118000
	v_cvt_pk_bf16_f32 v103, v103, s0
	v_cvt_pk_bf16_f32 v79, v79, s0
	v_lshl_add_u64 v[150:151], v[144:145], 0, s[98:99]
	global_store_short v[150:151], v103, off
	global_store_short v[150:151], v79, off offset:256
	s_mov_b32 s98, 0x258000
	v_cvt_pk_bf16_f32 v95, v95, s0
	v_cvt_pk_bf16_f32 v75, v75, s0
	v_lshl_add_u64 v[150:151], v[144:145], 0, s[98:99]
	global_store_short v[150:151], v95, off
	global_store_short v[150:151], v75, off offset:256
	s_mov_b32 s98, 0x398000
	v_cvt_pk_bf16_f32 v87, v87, s0
	v_cvt_pk_bf16_f32 v71, v71, s0
	v_lshl_add_u64 v[150:151], v[144:145], 0, s[98:99]
	global_store_short v[150:151], v87, off
	global_store_short v[150:151], v71, off offset:256
	s_mov_b32 s98, 0x4d8000
	v_cvt_pk_bf16_f32 v83, v83, s0
	v_cvt_pk_bf16_f32 v67, v67, s0
	v_lshl_add_u64 v[150:151], v[144:145], 0, s[98:99]
	global_store_short v[150:151], v83, off
	global_store_short v[150:151], v67, off offset:256
	v_permlane32_swap_b32_e32 v60, v52
	v_permlane32_swap_b32_e32 v56, v48
	v_permlane32_swap_b32_e32 v44, v32
	v_permlane32_swap_b32_e32 v40, v24
	v_permlane16_swap_b32_e32 v60, v56
	v_permlane16_swap_b32_e32 v52, v48
	v_permlane16_swap_b32_e32 v44, v40
	v_permlane16_swap_b32_e32 v32, v24
	s_mov_b32 s98, 0x1400000
	v_cvt_pk_bf16_f32 v60, v60, s0
	v_cvt_pk_bf16_f32 v44, v44, s0
	v_lshl_add_u64 v[150:151], v[144:145], 0, s[98:99]
	global_store_short v[150:151], v60, off
	global_store_short v[150:151], v44, off offset:256
	s_mov_b32 s98, 0x1540000
	v_cvt_pk_bf16_f32 v56, v56, s0
	v_cvt_pk_bf16_f32 v40, v40, s0
	v_lshl_add_u64 v[150:151], v[144:145], 0, s[98:99]
	global_store_short v[150:151], v56, off
	global_store_short v[150:151], v40, off offset:256
	s_mov_b32 s98, 0x1680000
	v_cvt_pk_bf16_f32 v52, v52, s0
	v_cvt_pk_bf16_f32 v32, v32, s0
; __device__ __forceinline__ bf16_t f2bf(float f) { return (bf16_t)cvtpk(f, 0.f); }
;     __device__ __forceinline__ void operator()(const f32x4 (&acc)[2][2][4][2], const pg8::Unit& u, int wr, int wc, int, int) const {
;     ...
;         if (u.pn < 6) {
;             bf16_t* cp = uhy + (size_t)(u.pn * 256 + wc * 32 + 8 * fq) * NTOK + row0;
; #pragma unroll
;             for (int bj = 0; bj < 2; ++bj)
; #pragma unroll
;                 for (int n = 0; n < 2; ++n)
; #pragma unroll
;                     for (int j = 0; j < 4; ++j) { bf16_t* q = cp + (size_t)(bj * HALF + 4 * n + j) * NTOK;
; #pragma unroll
;                         for (int ai = 0; ai < 2; ++ai)
; #pragma unroll
;                             for (int m = 0; m < 4; ++m) q[ai * HALF + m * 16] = f2bf(acc[ai][bj][m][n][j]);
;                         asm volatile("" ::: "memory"); }
	v_lshl_add_u64 v[150:151], v[144:145], 0, s[98:99]
	global_store_short v[150:151], v52, off
	global_store_short v[150:151], v32, off offset:256
	s_mov_b32 s98, 0x17c0000
	v_cvt_pk_bf16_f32 v48, v48, s0
	v_cvt_pk_bf16_f32 v24, v24, s0
	v_lshl_add_u64 v[150:151], v[144:145], 0, s[98:99]
	global_store_short v[150:151], v48, off
	global_store_short v[150:151], v24, off offset:256
	v_permlane32_swap_b32_e32 v61, v53
	v_permlane32_swap_b32_e32 v57, v49
	v_permlane32_swap_b32_e32 v45, v33
	v_permlane32_swap_b32_e32 v41, v25
	v_permlane16_swap_b32_e32 v61, v57
	v_permlane16_swap_b32_e32 v53, v49
	v_permlane16_swap_b32_e32 v45, v41
	v_permlane16_swap_b32_e32 v33, v25
	s_mov_b32 s98, 0x1428000
	v_cvt_pk_bf16_f32 v61, v61, s0
	v_cvt_pk_bf16_f32 v45, v45, s0
	v_lshl_add_u64 v[150:151], v[144:145], 0, s[98:99]
	global_store_short v[150:151], v61, off
	global_store_short v[150:151], v45, off offset:256
	s_mov_b32 s98, 0x1568000
	v_cvt_pk_bf16_f32 v57, v57, s0
	v_cvt_pk_bf16_f32 v41, v41, s0
	v_lshl_add_u64 v[150:151], v[144:145], 0, s[98:99]
	global_store_short v[150:151], v57, off
	global_store_short v[150:151], v41, off offset:256
	s_mov_b32 s98, 0x16a8000
	v_cvt_pk_bf16_f32 v53, v53, s0
	v_cvt_pk_bf16_f32 v33, v33, s0
	v_lshl_add_u64 v[150:151], v[144:145], 0, s[98:99]
	global_store_short v[150:151], v53, off
	global_store_short v[150:151], v33, off offset:256
	s_mov_b32 s98, 0x17e8000
	v_cvt_pk_bf16_f32 v49, v49, s0
	v_cvt_pk_bf16_f32 v25, v25, s0
	v_lshl_add_u64 v[150:151], v[144:145], 0, s[98:99]
	global_store_short v[150:151], v49, off
	global_store_short v[150:151], v25, off offset:256
	v_permlane32_swap_b32_e32 v62, v54
	v_permlane32_swap_b32_e32 v58, v50
	v_permlane32_swap_b32_e32 v46, v34
	v_permlane32_swap_b32_e32 v42, v26
	v_permlane16_swap_b32_e32 v62, v58
	v_permlane16_swap_b32_e32 v54, v50
	v_permlane16_swap_b32_e32 v46, v42
	v_permlane16_swap_b32_e32 v34, v26
	s_mov_b32 s98, 0x1450000
	v_cvt_pk_bf16_f32 v62, v62, s0
	v_cvt_pk_bf16_f32 v46, v46, s0
	v_lshl_add_u64 v[150:151], v[144:145], 0, s[98:99]
	global_store_short v[150:151], v62, off
	global_store_short v[150:151], v46, off offset:256
	s_mov_b32 s98, 0x1590000
	v_cvt_pk_bf16_f32 v58, v58, s0
	v_cvt_pk_bf16_f32 v42, v42, s0
	v_lshl_add_u64 v[150:151], v[144:145], 0, s[98:99]
	global_store_short v[150:151], v58, off
	global_store_short v[150:151], v42, off offset:256
	s_mov_b32 s98, 0x16d0000
	v_cvt_pk_bf16_f32 v54, v54, s0
	v_cvt_pk_bf16_f32 v34, v34, s0
	v_lshl_add_u64 v[150:151], v[144:145], 0, s[98:99]
	global_store_short v[150:151], v54, off
	global_store_short v[150:151], v34, off offset:256
	s_mov_b32 s98, 0x1810000
	v_cvt_pk_bf16_f32 v50, v50, s0
	v_cvt_pk_bf16_f32 v26, v26, s0
	v_lshl_add_u64 v[150:151], v[144:145], 0, s[98:99]
	global_store_short v[150:151], v50, off
	global_store_short v[150:151], v26, off offset:256
	v_permlane32_swap_b32_e32 v63, v55
	v_permlane32_swap_b32_e32 v59, v51
	v_permlane32_swap_b32_e32 v47, v35
	v_permlane32_swap_b32_e32 v43, v27
	v_permlane16_swap_b32_e32 v63, v59
	v_permlane16_swap_b32_e32 v55, v51
	v_permlane16_swap_b32_e32 v47, v43
	v_permlane16_swap_b32_e32 v35, v27
	s_mov_b32 s98, 0x1478000
	v_cvt_pk_bf16_f32 v63, v63, s0
	v_cvt_pk_bf16_f32 v47, v47, s0
	v_lshl_add_u64 v[150:151], v[144:145], 0, s[98:99]
	global_store_short v[150:151], v63, off
	global_store_short v[150:151], v47, off offset:256
	s_mov_b32 s98, 0x15b8000
	v_cvt_pk_bf16_f32 v59, v59, s0
	v_cvt_pk_bf16_f32 v43, v43, s0
	v_lshl_add_u64 v[150:151], v[144:145], 0, s[98:99]
	global_store_short v[150:151], v59, off
	global_store_short v[150:151], v43, off offset:256
	s_mov_b32 s98, 0x16f8000
	v_cvt_pk_bf16_f32 v55, v55, s0
	v_cvt_pk_bf16_f32 v35, v35, s0
	v_lshl_add_u64 v[150:151], v[144:145], 0, s[98:99]
	global_store_short v[150:151], v55, off
	global_store_short v[150:151], v35, off offset:256
	s_mov_b32 s98, 0x1838000
	v_cvt_pk_bf16_f32 v51, v51, s0
	v_cvt_pk_bf16_f32 v27, v27, s0
	v_lshl_add_u64 v[150:151], v[144:145], 0, s[98:99]
	global_store_short v[150:151], v51, off
	global_store_short v[150:151], v27, off offset:256
	v_permlane32_swap_b32_e32 v36, v20
	v_permlane32_swap_b32_e32 v28, v16
	v_permlane32_swap_b32_e32 v12, v4
	v_permlane32_swap_b32_e32 v8, v0
	v_permlane16_swap_b32_e32 v36, v28
	v_permlane16_swap_b32_e32 v20, v16
	v_permlane16_swap_b32_e32 v12, v8
	v_permlane16_swap_b32_e32 v4, v0
	s_mov_b32 s98, 0x14a0000
	v_cvt_pk_bf16_f32 v36, v36, s0
	v_cvt_pk_bf16_f32 v12, v12, s0
	v_lshl_add_u64 v[150:151], v[144:145], 0, s[98:99]
; __device__ __forceinline__ bf16_t f2bf(float f) { return (bf16_t)cvtpk(f, 0.f); }
;     __device__ __forceinline__ void operator()(const f32x4 (&acc)[2][2][4][2], const pg8::Unit& u, int wr, int wc, int, int) const {
;     ...
;         if (u.pn < 6) {
;             bf16_t* cp = uhy + (size_t)(u.pn * 256 + wc * 32 + 8 * fq) * NTOK + row0;
; #pragma unroll
;             for (int bj = 0; bj < 2; ++bj)
; #pragma unroll
;                 for (int n = 0; n < 2; ++n)
; #pragma unroll
;                     for (int j = 0; j < 4; ++j) { bf16_t* q = cp + (size_t)(bj * HALF + 4 * n + j) * NTOK;
; #pragma unroll
;                         for (int ai = 0; ai < 2; ++ai)
; #pragma unroll
;                             for (int m = 0; m < 4; ++m) q[ai * HALF + m * 16] = f2bf(acc[ai][bj][m][n][j]);
;                         asm volatile("" ::: "memory"); }
	global_store_short v[150:151], v36, off
	global_store_short v[150:151], v12, off offset:256
	s_mov_b32 s98, 0x15e0000
	v_cvt_pk_bf16_f32 v28, v28, s0
	v_cvt_pk_bf16_f32 v8, v8, s0
	v_lshl_add_u64 v[150:151], v[144:145], 0, s[98:99]
	global_store_short v[150:151], v28, off
	global_store_short v[150:151], v8, off offset:256
	s_mov_b32 s98, 0x1720000
	v_cvt_pk_bf16_f32 v20, v20, s0
	v_cvt_pk_bf16_f32 v4, v4, s0
	v_lshl_add_u64 v[150:151], v[144:145], 0, s[98:99]
	global_store_short v[150:151], v20, off
	global_store_short v[150:151], v4, off offset:256
	s_mov_b32 s98, 0x1860000
	v_cvt_pk_bf16_f32 v16, v16, s0
	v_cvt_pk_bf16_f32 v0, v0, s0
	v_lshl_add_u64 v[150:151], v[144:145], 0, s[98:99]
	global_store_short v[150:151], v16, off
	global_store_short v[150:151], v0, off offset:256
	v_permlane32_swap_b32_e32 v37, v21
	v_permlane32_swap_b32_e32 v29, v17
	v_permlane32_swap_b32_e32 v13, v5
	v_permlane32_swap_b32_e32 v9, v1
	v_permlane16_swap_b32_e32 v37, v29
	v_permlane16_swap_b32_e32 v21, v17
	v_permlane16_swap_b32_e32 v13, v9
	v_permlane16_swap_b32_e32 v5, v1
	s_mov_b32 s98, 0x14c8000
	v_cvt_pk_bf16_f32 v37, v37, s0
	v_cvt_pk_bf16_f32 v13, v13, s0
	v_lshl_add_u64 v[150:151], v[144:145], 0, s[98:99]
	global_store_short v[150:151], v37, off
	global_store_short v[150:151], v13, off offset:256
	s_mov_b32 s98, 0x1608000
	v_cvt_pk_bf16_f32 v29, v29, s0
	v_cvt_pk_bf16_f32 v9, v9, s0
	v_lshl_add_u64 v[150:151], v[144:145], 0, s[98:99]
	global_store_short v[150:151], v29, off
	global_store_short v[150:151], v9, off offset:256
	s_mov_b32 s98, 0x1748000
	v_cvt_pk_bf16_f32 v21, v21, s0
	v_cvt_pk_bf16_f32 v5, v5, s0
	v_lshl_add_u64 v[150:151], v[144:145], 0, s[98:99]
	global_store_short v[150:151], v21, off
	global_store_short v[150:151], v5, off offset:256
	s_mov_b32 s98, 0x1888000
	v_cvt_pk_bf16_f32 v17, v17, s0
	v_cvt_pk_bf16_f32 v1, v1, s0
	v_lshl_add_u64 v[150:151], v[144:145], 0, s[98:99]
	global_store_short v[150:151], v17, off
	global_store_short v[150:151], v1, off offset:256
	v_permlane32_swap_b32_e32 v38, v22
	v_permlane32_swap_b32_e32 v30, v18
	v_permlane32_swap_b32_e32 v14, v6
	v_permlane32_swap_b32_e32 v10, v2
	v_permlane16_swap_b32_e32 v38, v30
	v_permlane16_swap_b32_e32 v22, v18
	v_permlane16_swap_b32_e32 v14, v10
	v_permlane16_swap_b32_e32 v6, v2
	s_mov_b32 s98, 0x14f0000
	v_cvt_pk_bf16_f32 v38, v38, s0
	v_cvt_pk_bf16_f32 v14, v14, s0
	v_lshl_add_u64 v[150:151], v[144:145], 0, s[98:99]
	global_store_short v[150:151], v38, off
	global_store_short v[150:151], v14, off offset:256
	s_mov_b32 s98, 0x1630000
	v_cvt_pk_bf16_f32 v30, v30, s0
	v_cvt_pk_bf16_f32 v10, v10, s0
	v_lshl_add_u64 v[150:151], v[144:145], 0, s[98:99]
	global_store_short v[150:151], v30, off
	global_store_short v[150:151], v10, off offset:256
	s_mov_b32 s98, 0x1770000
	v_cvt_pk_bf16_f32 v22, v22, s0
	v_cvt_pk_bf16_f32 v6, v6, s0
	v_lshl_add_u64 v[150:151], v[144:145], 0, s[98:99]
	global_store_short v[150:151], v22, off
	global_store_short v[150:151], v6, off offset:256
	s_mov_b32 s98, 0x18b0000
	v_cvt_pk_bf16_f32 v18, v18, s0
	v_cvt_pk_bf16_f32 v2, v2, s0
	v_lshl_add_u64 v[150:151], v[144:145], 0, s[98:99]
	global_store_short v[150:151], v18, off
	global_store_short v[150:151], v2, off offset:256
	v_permlane32_swap_b32_e32 v39, v23
	v_permlane32_swap_b32_e32 v31, v19
	v_permlane32_swap_b32_e32 v15, v7
	v_permlane32_swap_b32_e32 v11, v3
	v_permlane16_swap_b32_e32 v39, v31
	v_permlane16_swap_b32_e32 v23, v19
	v_permlane16_swap_b32_e32 v15, v11
	v_permlane16_swap_b32_e32 v7, v3
	s_mov_b32 s98, 0x1518000
	v_cvt_pk_bf16_f32 v39, v39, s0
	v_cvt_pk_bf16_f32 v15, v15, s0
	v_lshl_add_u64 v[150:151], v[144:145], 0, s[98:99]
	global_store_short v[150:151], v39, off
	global_store_short v[150:151], v15, off offset:256
	s_mov_b32 s98, 0x1658000
	v_cvt_pk_bf16_f32 v31, v31, s0
	v_cvt_pk_bf16_f32 v11, v11, s0
	v_lshl_add_u64 v[150:151], v[144:145], 0, s[98:99]
	global_store_short v[150:151], v31, off
	global_store_short v[150:151], v11, off offset:256
	s_mov_b32 s98, 0x1798000
	v_cvt_pk_bf16_f32 v23, v23, s0
	v_cvt_pk_bf16_f32 v7, v7, s0
	v_lshl_add_u64 v[150:151], v[144:145], 0, s[98:99]
	global_store_short v[150:151], v23, off
	global_store_short v[150:151], v7, off offset:256
	s_mov_b32 s98, 0x18d8000
	v_cvt_pk_bf16_f32 v19, v19, s0
	v_cvt_pk_bf16_f32 v3, v3, s0
	v_lshl_add_u64 v[150:151], v[144:145], 0, s[98:99]
	global_store_short v[150:151], v19, off
	global_store_short v[150:151], v3, off offset:256
	s_branch .LBB0_172
